# attention: running row max pre-subtracted through the score MFMAs' initial accumulator (no per-element subtract on the common path), probabilities packed in place, lazy exact-max update
# baseline (speedup 1.0000x reference)
.Lat_item:
	s_and_b32 s0, s34, 7
	s_ashr_i32 s12, s34, 7
	s_lshl_b32 s13, s34, 5
	s_and_b32 s13, s13, 0xf00
	s_lshl_b32 s1, s12, 12
	s_or_b32 s13, s13, s1
	s_lshl_b32 s1, s12, 3
	s_or_b32 s1, s1, s0
	s_mul_i32 s1, s1, 0x110000
	s_add_u32 s36, s22, s1
	s_addc_u32 s37, s23, 0
	s_add_u32 s42, s26, s1
	s_addc_u32 s43, s27, 0
	s_mul_i32 s1, s12, 0x88000
	s_add_u32 s38, s24, s1
	s_addc_u32 s39, s25, 0
	v_and_b32_e32 v253, 15, v167
	v_bfe_u32 v199, v167, 4, 2
	v_lshrrev_b32_e32 v200, 4, v167
	v_lshrrev_b32_e32 v201, 3, v167
	v_and_b32_e32 v252, 7, v167
	v_lshlrev_b32_e32 v172, 8, v200
	v_lshl_add_u32 v172, v253, 4, v172
	v_add_u32_e32 v173, 0x2000, v172
	v_lshlrev_b32_e32 v174, 7, v201
	v_lshl_add_u32 v174, v252, 4, v174
	v_mul_u32_u24_e32 v175, 0x2200, v201
	v_lshl_add_u32 v175, v252, 4, v175
	v_add_u32_e32 v176, 0x88000, v175
	global_load_dwordx4 v[112:115], v172, s[36:37]
	global_load_dwordx4 v[116:119], v173, s[36:37]
	global_load_dwordx4 v[120:123], v174, s[38:39]
	global_load_dwordx4 v[124:127], v175, s[42:43]
	global_load_dwordx4 v[128:131], v176, s[42:43]
	s_mul_i32 s1, s13, 0xc00
	s_mul_i32 s0, s0, 0x180
	s_add_u32 s1, s1, s0
	s_add_u32 s0, s20, s1
	s_addc_u32 s1, s21, 0
	v_lshrrev_b32_e32 v193, 6, v167
	v_lshl_add_u32 v193, v193, 5, v253
	v_mul_u32_u24_e32 v193, 0xc00, v193
	v_lshl_add_u32 v193, v199, 4, v193
	v_add_u32_e32 v194, 0xc000, v193
	global_load_dwordx4 v[64:67], v193, s[0:1]
	global_load_dwordx4 v[68:71], v193, s[0:1] offset:64
	global_load_dwordx4 v[72:75], v193, s[0:1] offset:128
	global_load_dwordx4 v[76:79], v193, s[0:1] offset:192
	global_load_dwordx4 v[80:83], v193, s[0:1] offset:256
	global_load_dwordx4 v[84:87], v193, s[0:1] offset:320
	global_load_dwordx4 v[88:91], v194, s[0:1]
	global_load_dwordx4 v[92:95], v194, s[0:1] offset:64
	global_load_dwordx4 v[96:99], v194, s[0:1] offset:128
	global_load_dwordx4 v[100:103], v194, s[0:1] offset:192
	global_load_dwordx4 v[104:107], v194, s[0:1] offset:256
	global_load_dwordx4 v[108:111], v194, s[0:1] offset:320
	v_mul_u32_u24_e32 v164, 416, v253
	v_lshl_add_u32 v164, v199, 4, v164
	v_mul_u32_u24_e32 v168, 160, v253
	v_lshl_add_u32 v168, v199, 4, v168
	v_mul_u32_u24_e32 v169, 416, v200
	v_lshl_add_u32 v169, v253, 4, v169
	v_mul_u32_u24_e32 v170, 416, v201
	v_lshl_add_u32 v170, v252, 4, v170
	v_add_u32_e32 v170, 0x100, v170
	v_mul_u32_u24_e32 v171, 160, v201
	v_lshrrev_b32_e32 v200, 2, v252
	v_lshl_add_u32 v171, v200, 6, v171
	v_and_b32_e32 v200, 1, v252
	v_lshl_add_u32 v171, v200, 5, v171
	v_bfe_u32 v200, v252, 1, 1
	v_lshl_add_u32 v171, v200, 3, v171
	v_mov_b32_e32 v0, 0
	v_mov_b32_e32 v1, 0
	v_mov_b32_e32 v2, 0
	v_mov_b32_e32 v3, 0
	v_mov_b32_e32 v4, 0
	v_mov_b32_e32 v5, 0
	v_mov_b32_e32 v6, 0
	v_mov_b32_e32 v7, 0
	v_mov_b32_e32 v8, 0
	v_mov_b32_e32 v9, 0
	v_mov_b32_e32 v10, 0
	v_mov_b32_e32 v11, 0
	v_mov_b32_e32 v12, 0
	v_mov_b32_e32 v13, 0
	v_mov_b32_e32 v14, 0
	v_mov_b32_e32 v15, 0
	v_mov_b32_e32 v16, 0
	v_mov_b32_e32 v17, 0
	v_mov_b32_e32 v18, 0
	v_mov_b32_e32 v19, 0
	v_mov_b32_e32 v20, 0
	v_mov_b32_e32 v21, 0
	v_mov_b32_e32 v22, 0
	v_mov_b32_e32 v23, 0
	v_mov_b32_e32 v24, 0
	v_mov_b32_e32 v25, 0
	v_mov_b32_e32 v26, 0
	v_mov_b32_e32 v27, 0
	v_mov_b32_e32 v28, 0
	v_mov_b32_e32 v29, 0
	v_mov_b32_e32 v30, 0
	v_mov_b32_e32 v31, 0
	v_mov_b32_e32 v32, 0
	v_mov_b32_e32 v33, 0
	v_mov_b32_e32 v34, 0
	v_mov_b32_e32 v35, 0
	v_mov_b32_e32 v36, 0
	v_mov_b32_e32 v37, 0
	v_mov_b32_e32 v38, 0
	v_mov_b32_e32 v39, 0
	v_mov_b32_e32 v40, 0
	v_mov_b32_e32 v41, 0
	v_mov_b32_e32 v42, 0
	v_mov_b32_e32 v43, 0
	v_mov_b32_e32 v44, 0
	v_mov_b32_e32 v45, 0
	v_mov_b32_e32 v46, 0
	v_mov_b32_e32 v47, 0
	v_mov_b32_e32 v48, 0
	v_mov_b32_e32 v49, 0
	v_mov_b32_e32 v50, 0
	v_mov_b32_e32 v51, 0
	v_mov_b32_e32 v52, 0
	v_mov_b32_e32 v53, 0
	v_mov_b32_e32 v54, 0
	v_mov_b32_e32 v55, 0
	v_mov_b32_e32 v56, 0
	v_mov_b32_e32 v57, 0
	v_mov_b32_e32 v58, 0
	v_mov_b32_e32 v59, 0
	v_mov_b32_e32 v60, 0
	v_mov_b32_e32 v61, 0
	v_mov_b32_e32 v62, 0
	v_mov_b32_e32 v63, 0
	v_mov_b32_e32 v236, 0
	v_mov_b32_e32 v237, 0
	v_mov_b32_e32 v238, 0
	v_mov_b32_e32 v239, 0
	v_mov_b32_e32 v240, 0
	v_mov_b32_e32 v241, 0
	v_mov_b32_e32 v242, 0
	v_mov_b32_e32 v243, 0
	v_mov_b32_e32 v244, 0xf149f2ca
	v_mov_b32_e32 v179, 0
	v_mov_b32_e32 v180, 0
	s_mov_b32 s35, 0
	s_mov_b32 s44, 0
	s_mov_b32 s0, 94208
	s_mov_b32 s1, 53248
	s_mov_b32 s13, 73728
	s_waitcnt vmcnt(12)
	ds_write_b128 v169, v[112:115]
	ds_write_b128 v169, v[116:119] offset:13312
	ds_write_b128 v170, v[120:123]
	v_add_u32_e32 v197, 53248, v171
	v_add_u32_e32 v198, 10240, v197
	ds_write2_b64 v197, v[124:125], v[126:127] offset1:2
	ds_write2_b64 v198, v[128:129], v[130:131] offset1:2
	v_readfirstlane_b32 s12, v167
	s_waitcnt vmcnt(0) lgkmcnt(0)
	s_barrier
	s_cmpk_lt_u32 s12, 256
	s_cbranch_scc0 .Lat_B_entry

.Lat_noload_A:
	v_add_u32_e32 v193, s44, v164
	v_add_u32_e32 v194, s1, v168
	s_setprio 0
	ds_read_b128 v[204:207], v193
	ds_read_b128 v[208:211], v193 offset:6656
	ds_read_b128 v[212:215], v193 offset:13312
	ds_read_b128 v[216:219], v193 offset:19968
	ds_read_b128 v[220:223], v193 offset:64
	ds_read_b128 v[224:227], v193 offset:6720
	ds_read_b128 v[228:231], v193 offset:13376
	ds_read_b128 v[232:235], v193 offset:20032
	s_waitcnt lgkmcnt(7)
	v_mfma_f32_16x16x32_bf16 v[132:135], v[204:207], v[64:67], v[236:239]
	v_mfma_f32_16x16x32_bf16 v[136:139], v[204:207], v[88:91], v[240:243]
	ds_read_b128 v[204:207], v193 offset:128
	s_waitcnt lgkmcnt(7)
	v_mfma_f32_16x16x32_bf16 v[140:143], v[208:211], v[64:67], v[236:239]
	v_mfma_f32_16x16x32_bf16 v[144:147], v[208:211], v[88:91], v[240:243]
	ds_read_b128 v[208:211], v193 offset:6784
	s_waitcnt lgkmcnt(7)
	v_mfma_f32_16x16x32_bf16 v[148:151], v[212:215], v[64:67], v[236:239]
	v_mfma_f32_16x16x32_bf16 v[152:155], v[212:215], v[88:91], v[240:243]
	ds_read_b128 v[212:215], v193 offset:13440
	s_waitcnt lgkmcnt(7)
	v_mfma_f32_16x16x32_bf16 v[156:159], v[216:219], v[64:67], v[236:239]
	v_mfma_f32_16x16x32_bf16 v[160:163], v[216:219], v[88:91], v[240:243]
	ds_read_b128 v[216:219], v193 offset:20096
	s_waitcnt lgkmcnt(7)
	v_mfma_f32_16x16x32_bf16 v[132:135], v[220:223], v[68:71], v[132:135]
	v_mfma_f32_16x16x32_bf16 v[136:139], v[220:223], v[92:95], v[136:139]
	ds_read_b128 v[220:223], v193 offset:192
	s_waitcnt lgkmcnt(7)
	v_mfma_f32_16x16x32_bf16 v[140:143], v[224:227], v[68:71], v[140:143]
	v_mfma_f32_16x16x32_bf16 v[144:147], v[224:227], v[92:95], v[144:147]
	ds_read_b128 v[224:227], v193 offset:6848
	s_waitcnt lgkmcnt(7)
	v_mfma_f32_16x16x32_bf16 v[148:151], v[228:231], v[68:71], v[148:151]
	v_mfma_f32_16x16x32_bf16 v[152:155], v[228:231], v[92:95], v[152:155]
	ds_read_b128 v[228:231], v193 offset:13504
	s_waitcnt lgkmcnt(7)
	v_mfma_f32_16x16x32_bf16 v[156:159], v[232:235], v[68:71], v[156:159]
	v_mfma_f32_16x16x32_bf16 v[160:163], v[232:235], v[92:95], v[160:163]
	ds_read_b128 v[232:235], v193 offset:20160
	s_waitcnt lgkmcnt(7)
	v_mfma_f32_16x16x32_bf16 v[132:135], v[204:207], v[72:75], v[132:135]
	v_mfma_f32_16x16x32_bf16 v[136:139], v[204:207], v[96:99], v[136:139]
	ds_read_b128 v[204:207], v193 offset:256
	s_waitcnt lgkmcnt(7)
	v_mfma_f32_16x16x32_bf16 v[140:143], v[208:211], v[72:75], v[140:143]
	v_mfma_f32_16x16x32_bf16 v[144:147], v[208:211], v[96:99], v[144:147]
	ds_read_b128 v[208:211], v193 offset:6912
	s_waitcnt lgkmcnt(7)
	v_mfma_f32_16x16x32_bf16 v[148:151], v[212:215], v[72:75], v[148:151]
	v_mfma_f32_16x16x32_bf16 v[152:155], v[212:215], v[96:99], v[152:155]
	ds_read_b128 v[212:215], v193 offset:13568
	s_waitcnt lgkmcnt(7)
	v_mfma_f32_16x16x32_bf16 v[156:159], v[216:219], v[72:75], v[156:159]
	v_mfma_f32_16x16x32_bf16 v[160:163], v[216:219], v[96:99], v[160:163]
	ds_read_b128 v[216:219], v193 offset:20224
	s_waitcnt lgkmcnt(7)
	v_mfma_f32_16x16x32_bf16 v[132:135], v[220:223], v[76:79], v[132:135]
	v_mfma_f32_16x16x32_bf16 v[136:139], v[220:223], v[100:103], v[136:139]
	ds_read_b128 v[220:223], v193 offset:320
	s_waitcnt lgkmcnt(7)
	v_mfma_f32_16x16x32_bf16 v[140:143], v[224:227], v[76:79], v[140:143]
	v_mfma_f32_16x16x32_bf16 v[144:147], v[224:227], v[100:103], v[144:147]
	ds_read_b128 v[224:227], v193 offset:6976
	s_waitcnt lgkmcnt(7)
	v_mfma_f32_16x16x32_bf16 v[148:151], v[228:231], v[76:79], v[148:151]
	v_mfma_f32_16x16x32_bf16 v[152:155], v[228:231], v[100:103], v[152:155]
	ds_read_b128 v[228:231], v193 offset:13632
	s_waitcnt lgkmcnt(7)
	v_mfma_f32_16x16x32_bf16 v[156:159], v[232:235], v[76:79], v[156:159]
	v_mfma_f32_16x16x32_bf16 v[160:163], v[232:235], v[100:103], v[160:163]
	ds_read_b128 v[232:235], v193 offset:20288
	s_waitcnt lgkmcnt(7)
	v_mfma_f32_16x16x32_bf16 v[132:135], v[204:207], v[80:83], v[132:135]
	v_mfma_f32_16x16x32_bf16 v[136:139], v[204:207], v[104:107], v[136:139]
	ds_read_b128 v[204:207], v194
	s_waitcnt lgkmcnt(7)
	v_mfma_f32_16x16x32_bf16 v[140:143], v[208:211], v[80:83], v[140:143]
	v_mfma_f32_16x16x32_bf16 v[144:147], v[208:211], v[104:107], v[144:147]
	ds_read_b128 v[208:211], v194 offset:64
	s_waitcnt lgkmcnt(7)
	v_mfma_f32_16x16x32_bf16 v[148:151], v[212:215], v[80:83], v[148:151]
	v_mfma_f32_16x16x32_bf16 v[152:155], v[212:215], v[104:107], v[152:155]
	ds_read_b128 v[212:215], v194 offset:2560
	s_waitcnt lgkmcnt(7)
	v_mfma_f32_16x16x32_bf16 v[156:159], v[216:219], v[80:83], v[156:159]
	v_mfma_f32_16x16x32_bf16 v[160:163], v[216:219], v[104:107], v[160:163]
	ds_read_b128 v[216:219], v194 offset:2624
	s_waitcnt lgkmcnt(7)
	v_mfma_f32_16x16x32_bf16 v[132:135], v[220:223], v[84:87], v[132:135]
	v_mfma_f32_16x16x32_bf16 v[136:139], v[220:223], v[108:111], v[136:139]
	ds_read_b128 v[220:223], v194 offset:5120
	s_waitcnt lgkmcnt(7)
	v_mfma_f32_16x16x32_bf16 v[140:143], v[224:227], v[84:87], v[140:143]
	v_mfma_f32_16x16x32_bf16 v[144:147], v[224:227], v[108:111], v[144:147]
	ds_read_b128 v[224:227], v194 offset:5184
	s_waitcnt lgkmcnt(7)
	v_mfma_f32_16x16x32_bf16 v[148:151], v[228:231], v[84:87], v[148:151]
	v_mfma_f32_16x16x32_bf16 v[152:155], v[228:231], v[108:111], v[152:155]
	ds_read_b128 v[228:231], v194 offset:7680
	s_waitcnt lgkmcnt(7)
	v_mfma_f32_16x16x32_bf16 v[156:159], v[232:235], v[84:87], v[156:159]
	v_mfma_f32_16x16x32_bf16 v[160:163], v[232:235], v[108:111], v[160:163]
	ds_read_b128 v[232:235], v194 offset:7744
	s_setprio 1
	s_nop 6
	v_max3_f32 v199, v132, v133, v134
	v_max3_f32 v200, v136, v137, v138
	v_max3_f32 v199, v199, v135, v140
	v_max3_f32 v200, v200, v139, v144
	v_max3_f32 v199, v199, v141, v142
	v_max3_f32 v200, v200, v145, v146
	v_max3_f32 v199, v199, v143, v148
	v_max3_f32 v200, v200, v147, v152
	v_max3_f32 v199, v199, v149, v150
	v_max3_f32 v200, v200, v153, v154
	v_max3_f32 v199, v199, v151, v156
	v_max3_f32 v200, v200, v155, v160
	v_max3_f32 v199, v199, v157, v158
	v_max3_f32 v200, v200, v161, v162
	v_max_f32_e32 v199, v199, v159
	v_max_f32_e32 v200, v200, v163
	v_mov_b32_e32 v253, v199
	v_mov_b32_e32 v201, v200
	s_nop 1
	v_permlane16_swap_b32_e32 v199, v253
	v_permlane16_swap_b32_e32 v200, v201
	s_nop 0
	v_max_f32_e32 v199, v199, v253
	v_max_f32_e32 v200, v200, v201
	v_mov_b32_e32 v253, v199
	v_mov_b32_e32 v201, v200
	s_nop 1
	v_permlane32_swap_b32_e32 v199, v253
	v_permlane32_swap_b32_e32 v200, v201
	s_nop 0
	v_max_f32_e32 v199, v199, v253
	v_max_f32_e32 v200, v200, v201
	v_max_f32_e32 v253, v199, v200
	v_cmp_lt_f32_e32 vcc, v244, v253
	s_cbranch_vccz .Lat_fast_A
	v_cmp_lt_f32_e32 vcc, v244, v199
	s_nop 1
	v_cndmask_b32_e32 v199, 0, v199, vcc
	v_max_f32_e32 v182, 0, v199
	v_exp_f32_e64 v182, -v182
	v_sub_f32_e32 v132, v132, v199
	v_sub_f32_e32 v133, v133, v199
	v_sub_f32_e32 v134, v134, v199
	v_sub_f32_e32 v135, v135, v199
	v_sub_f32_e32 v140, v140, v199
	v_sub_f32_e32 v141, v141, v199
	v_sub_f32_e32 v142, v142, v199
	v_sub_f32_e32 v143, v143, v199
	v_sub_f32_e32 v148, v148, v199
	v_sub_f32_e32 v149, v149, v199
	v_sub_f32_e32 v150, v150, v199
	v_sub_f32_e32 v151, v151, v199
	v_sub_f32_e32 v156, v156, v199
	v_sub_f32_e32 v157, v157, v199
	v_sub_f32_e32 v158, v158, v199
	v_sub_f32_e32 v159, v159, v199
	v_sub_f32_e32 v236, v236, v199
	v_sub_f32_e32 v237, v237, v199
	v_sub_f32_e32 v238, v238, v199
	v_sub_f32_e32 v239, v239, v199
	v_pk_mul_f32 v[0:1], v[0:1], v[182:183] op_sel_hi:[1,0]
	v_pk_mul_f32 v[2:3], v[2:3], v[182:183] op_sel_hi:[1,0]
	v_pk_mul_f32 v[8:9], v[8:9], v[182:183] op_sel_hi:[1,0]
	v_pk_mul_f32 v[10:11], v[10:11], v[182:183] op_sel_hi:[1,0]
	v_pk_mul_f32 v[16:17], v[16:17], v[182:183] op_sel_hi:[1,0]
	v_pk_mul_f32 v[18:19], v[18:19], v[182:183] op_sel_hi:[1,0]
	v_pk_mul_f32 v[24:25], v[24:25], v[182:183] op_sel_hi:[1,0]
	v_pk_mul_f32 v[26:27], v[26:27], v[182:183] op_sel_hi:[1,0]
	v_pk_mul_f32 v[32:33], v[32:33], v[182:183] op_sel_hi:[1,0]
	v_pk_mul_f32 v[34:35], v[34:35], v[182:183] op_sel_hi:[1,0]
	v_pk_mul_f32 v[40:41], v[40:41], v[182:183] op_sel_hi:[1,0]
	v_pk_mul_f32 v[42:43], v[42:43], v[182:183] op_sel_hi:[1,0]
	v_pk_mul_f32 v[48:49], v[48:49], v[182:183] op_sel_hi:[1,0]
	v_pk_mul_f32 v[50:51], v[50:51], v[182:183] op_sel_hi:[1,0]
	v_pk_mul_f32 v[56:57], v[56:57], v[182:183] op_sel_hi:[1,0]
	v_pk_mul_f32 v[58:59], v[58:59], v[182:183] op_sel_hi:[1,0]
	v_mul_f32_e32 v179, v179, v182
	v_cmp_lt_f32_e32 vcc, v244, v200
	s_nop 1
	v_cndmask_b32_e32 v200, 0, v200, vcc
	v_max_f32_e32 v202, 0, v200
	v_exp_f32_e64 v202, -v202
	v_sub_f32_e32 v136, v136, v200
	v_sub_f32_e32 v137, v137, v200
	v_sub_f32_e32 v138, v138, v200
	v_sub_f32_e32 v139, v139, v200
	v_sub_f32_e32 v144, v144, v200
	v_sub_f32_e32 v145, v145, v200
	v_sub_f32_e32 v146, v146, v200
	v_sub_f32_e32 v147, v147, v200
	v_sub_f32_e32 v152, v152, v200
	v_sub_f32_e32 v153, v153, v200
	v_sub_f32_e32 v154, v154, v200
	v_sub_f32_e32 v155, v155, v200
	v_sub_f32_e32 v160, v160, v200
	v_sub_f32_e32 v161, v161, v200
	v_sub_f32_e32 v162, v162, v200
	v_sub_f32_e32 v163, v163, v200
	v_sub_f32_e32 v240, v240, v200
	v_sub_f32_e32 v241, v241, v200
	v_sub_f32_e32 v242, v242, v200
	v_sub_f32_e32 v243, v243, v200
	v_pk_mul_f32 v[4:5], v[4:5], v[202:203] op_sel_hi:[1,0]
	v_pk_mul_f32 v[6:7], v[6:7], v[202:203] op_sel_hi:[1,0]
	v_pk_mul_f32 v[12:13], v[12:13], v[202:203] op_sel_hi:[1,0]
	v_pk_mul_f32 v[14:15], v[14:15], v[202:203] op_sel_hi:[1,0]
	v_pk_mul_f32 v[20:21], v[20:21], v[202:203] op_sel_hi:[1,0]
	v_pk_mul_f32 v[22:23], v[22:23], v[202:203] op_sel_hi:[1,0]
	v_pk_mul_f32 v[28:29], v[28:29], v[202:203] op_sel_hi:[1,0]
	v_pk_mul_f32 v[30:31], v[30:31], v[202:203] op_sel_hi:[1,0]
	v_pk_mul_f32 v[36:37], v[36:37], v[202:203] op_sel_hi:[1,0]
	v_pk_mul_f32 v[38:39], v[38:39], v[202:203] op_sel_hi:[1,0]
	v_pk_mul_f32 v[44:45], v[44:45], v[202:203] op_sel_hi:[1,0]
	v_pk_mul_f32 v[46:47], v[46:47], v[202:203] op_sel_hi:[1,0]
	v_pk_mul_f32 v[52:53], v[52:53], v[202:203] op_sel_hi:[1,0]
	v_pk_mul_f32 v[54:55], v[54:55], v[202:203] op_sel_hi:[1,0]
	v_pk_mul_f32 v[60:61], v[60:61], v[202:203] op_sel_hi:[1,0]
	v_pk_mul_f32 v[62:63], v[62:63], v[202:203] op_sel_hi:[1,0]
	v_mul_f32_e32 v180, v180, v202
	v_mov_b32_e32 v244, 0x41000000
.Lat_fast_A:
	v_exp_f32_e32 v132, v132
	v_exp_f32_e32 v136, v136
	v_exp_f32_e32 v133, v133
	v_exp_f32_e32 v137, v137
	v_exp_f32_e32 v134, v134
	v_exp_f32_e32 v138, v138
	v_exp_f32_e32 v135, v135
	v_exp_f32_e32 v139, v139
	v_exp_f32_e32 v140, v140
	v_exp_f32_e32 v144, v144
	v_exp_f32_e32 v141, v141
	v_exp_f32_e32 v145, v145
	v_exp_f32_e32 v142, v142
	v_exp_f32_e32 v146, v146
	v_exp_f32_e32 v143, v143
	v_exp_f32_e32 v147, v147
	v_exp_f32_e32 v148, v148
	v_exp_f32_e32 v152, v152
	v_exp_f32_e32 v149, v149
	v_exp_f32_e32 v153, v153
	v_exp_f32_e32 v150, v150
	v_exp_f32_e32 v154, v154
	v_exp_f32_e32 v151, v151
	v_exp_f32_e32 v155, v155
	v_exp_f32_e32 v156, v156
	v_exp_f32_e32 v160, v160
	v_exp_f32_e32 v157, v157
	v_exp_f32_e32 v161, v161
	v_exp_f32_e32 v158, v158
	v_exp_f32_e32 v162, v162
	v_exp_f32_e32 v159, v159
	v_exp_f32_e32 v163, v163
	v_add_f32_e32 v183, v132, v133
	v_add_f32_e32 v203, v136, v137
	v_add_f32_e32 v183, v183, v134
	v_add_f32_e32 v203, v203, v138
	v_add_f32_e32 v183, v183, v135
	v_add_f32_e32 v203, v203, v139
	v_add_f32_e32 v183, v183, v140
	v_add_f32_e32 v203, v203, v144
	v_add_f32_e32 v183, v183, v141
	v_add_f32_e32 v203, v203, v145
	v_add_f32_e32 v183, v183, v142
	v_add_f32_e32 v203, v203, v146
	v_add_f32_e32 v183, v183, v143
	v_add_f32_e32 v203, v203, v147
	v_add_f32_e32 v183, v183, v148
	v_add_f32_e32 v203, v203, v152
	v_add_f32_e32 v183, v183, v149
	v_add_f32_e32 v203, v203, v153
	v_add_f32_e32 v183, v183, v150
	v_add_f32_e32 v203, v203, v154
	v_add_f32_e32 v183, v183, v151
	v_add_f32_e32 v203, v203, v155
	v_add_f32_e32 v183, v183, v156
	v_add_f32_e32 v203, v203, v160
	v_add_f32_e32 v183, v183, v157
	v_add_f32_e32 v203, v203, v161
	v_add_f32_e32 v183, v183, v158
	v_add_f32_e32 v203, v203, v162
	v_add_f32_e32 v183, v183, v159
	v_add_f32_e32 v203, v203, v163
	v_add_f32_e32 v179, v179, v183
	v_add_f32_e32 v180, v180, v203
	v_cvt_pk_bf16_f32 v132, v132, v133
	v_cvt_pk_bf16_f32 v133, v134, v135
	v_cvt_pk_bf16_f32 v134, v140, v141
	v_cvt_pk_bf16_f32 v135, v142, v143
	v_cvt_pk_bf16_f32 v136, v136, v137
	v_cvt_pk_bf16_f32 v137, v138, v139
	v_cvt_pk_bf16_f32 v138, v144, v145
	v_cvt_pk_bf16_f32 v139, v146, v147
	v_cvt_pk_bf16_f32 v148, v148, v149
	v_cvt_pk_bf16_f32 v149, v150, v151
	v_cvt_pk_bf16_f32 v150, v156, v157
	v_cvt_pk_bf16_f32 v151, v158, v159
	v_cvt_pk_bf16_f32 v152, v152, v153
	v_cvt_pk_bf16_f32 v153, v154, v155
	v_cvt_pk_bf16_f32 v154, v160, v161
	v_cvt_pk_bf16_f32 v155, v162, v163
	s_setprio 0
	s_nop 0
	s_waitcnt lgkmcnt(7)
	v_mfma_f32_16x16x32_bf16 v[0:3], v[204:207], v[132:135], v[0:3]
	v_mfma_f32_16x16x32_bf16 v[4:7], v[204:207], v[136:139], v[4:7]
	ds_read_b128 v[204:207], v194 offset:10240
	s_waitcnt lgkmcnt(7)
	v_mfma_f32_16x16x32_bf16 v[0:3], v[208:211], v[148:151], v[0:3]
	v_mfma_f32_16x16x32_bf16 v[4:7], v[208:211], v[152:155], v[4:7]
	ds_read_b128 v[208:211], v194 offset:10304
	s_waitcnt lgkmcnt(7)
	v_mfma_f32_16x16x32_bf16 v[8:11], v[212:215], v[132:135], v[8:11]
	v_mfma_f32_16x16x32_bf16 v[12:15], v[212:215], v[136:139], v[12:15]
	ds_read_b128 v[212:215], v194 offset:12800
	s_waitcnt lgkmcnt(7)
	v_mfma_f32_16x16x32_bf16 v[8:11], v[216:219], v[148:151], v[8:11]
	v_mfma_f32_16x16x32_bf16 v[12:15], v[216:219], v[152:155], v[12:15]
	ds_read_b128 v[216:219], v194 offset:12864
	s_waitcnt lgkmcnt(7)
	v_mfma_f32_16x16x32_bf16 v[16:19], v[220:223], v[132:135], v[16:19]
	v_mfma_f32_16x16x32_bf16 v[20:23], v[220:223], v[136:139], v[20:23]
	ds_read_b128 v[220:223], v194 offset:15360
	s_waitcnt lgkmcnt(7)
	v_mfma_f32_16x16x32_bf16 v[16:19], v[224:227], v[148:151], v[16:19]
	v_mfma_f32_16x16x32_bf16 v[20:23], v[224:227], v[152:155], v[20:23]
	ds_read_b128 v[224:227], v194 offset:15424
	s_waitcnt lgkmcnt(7)
	v_mfma_f32_16x16x32_bf16 v[24:27], v[228:231], v[132:135], v[24:27]
	v_mfma_f32_16x16x32_bf16 v[28:31], v[228:231], v[136:139], v[28:31]
	ds_read_b128 v[228:231], v194 offset:17920
	s_waitcnt lgkmcnt(7)
	v_mfma_f32_16x16x32_bf16 v[24:27], v[232:235], v[148:151], v[24:27]
	v_mfma_f32_16x16x32_bf16 v[28:31], v[232:235], v[152:155], v[28:31]
	ds_read_b128 v[232:235], v194 offset:17984
	s_waitcnt lgkmcnt(7)
	v_mfma_f32_16x16x32_bf16 v[32:35], v[204:207], v[132:135], v[32:35]
	v_mfma_f32_16x16x32_bf16 v[36:39], v[204:207], v[136:139], v[36:39]
	s_waitcnt lgkmcnt(6)
	v_mfma_f32_16x16x32_bf16 v[32:35], v[208:211], v[148:151], v[32:35]
	v_mfma_f32_16x16x32_bf16 v[36:39], v[208:211], v[152:155], v[36:39]
	s_waitcnt lgkmcnt(5)
	v_mfma_f32_16x16x32_bf16 v[40:43], v[212:215], v[132:135], v[40:43]
	v_mfma_f32_16x16x32_bf16 v[44:47], v[212:215], v[136:139], v[44:47]
	s_waitcnt lgkmcnt(4)
	v_mfma_f32_16x16x32_bf16 v[40:43], v[216:219], v[148:151], v[40:43]
	v_mfma_f32_16x16x32_bf16 v[44:47], v[216:219], v[152:155], v[44:47]
	s_waitcnt lgkmcnt(3)
	v_mfma_f32_16x16x32_bf16 v[48:51], v[220:223], v[132:135], v[48:51]
	v_mfma_f32_16x16x32_bf16 v[52:55], v[220:223], v[136:139], v[52:55]
	s_waitcnt lgkmcnt(2)
	v_mfma_f32_16x16x32_bf16 v[48:51], v[224:227], v[148:151], v[48:51]
	v_mfma_f32_16x16x32_bf16 v[52:55], v[224:227], v[152:155], v[52:55]
	s_waitcnt lgkmcnt(1)
	v_mfma_f32_16x16x32_bf16 v[56:59], v[228:231], v[132:135], v[56:59]
	v_mfma_f32_16x16x32_bf16 v[60:63], v[228:231], v[136:139], v[60:63]
	s_waitcnt lgkmcnt(0)
	v_mfma_f32_16x16x32_bf16 v[56:59], v[232:235], v[148:151], v[56:59]
	v_mfma_f32_16x16x32_bf16 v[60:63], v[232:235], v[152:155], v[60:63]
	s_setprio 1
	s_cmpk_lt_u32 s35, 67
	s_cbranch_scc0 .Lat_nostage_A
	s_xor_b32 s12, s44, 26624
	v_add_u32_e32 v195, s12, v169
	v_add_u32_e32 v196, s12, v170
	v_add_u32_e32 v197, s13, v171
	v_add_u32_e32 v198, 10240, v197
	s_waitcnt vmcnt(0)
	ds_write_b128 v195, v[112:115]
	ds_write_b128 v195, v[116:119] offset:13312
	ds_write_b128 v196, v[120:123]
	ds_write2_b64 v197, v[124:125], v[126:127] offset1:2
	ds_write2_b64 v198, v[128:129], v[130:131] offset1:2

.Lat_noload_B0:
	v_add_u32_e32 v193, s44, v164
	v_add_u32_e32 v252, s1, v168
	s_setprio 0
	ds_read_b128 v[204:207], v193
	ds_read_b128 v[208:211], v193 offset:6656
	ds_read_b128 v[212:215], v193 offset:13312
	ds_read_b128 v[216:219], v193 offset:19968
	ds_read_b128 v[220:223], v193 offset:64
	ds_read_b128 v[224:227], v193 offset:6720
	ds_read_b128 v[228:231], v193 offset:13376
	ds_read_b128 v[232:235], v193 offset:20032
	s_waitcnt lgkmcnt(7)
	v_mfma_f32_16x16x32_bf16 v[132:135], v[204:207], v[64:67], v[236:239]
	v_mfma_f32_16x16x32_bf16 v[136:139], v[204:207], v[88:91], v[240:243]
	ds_read_b128 v[204:207], v193 offset:128
	s_waitcnt lgkmcnt(7)
	v_mfma_f32_16x16x32_bf16 v[140:143], v[208:211], v[64:67], v[236:239]
	v_mfma_f32_16x16x32_bf16 v[144:147], v[208:211], v[88:91], v[240:243]
	ds_read_b128 v[208:211], v193 offset:6784
	s_waitcnt lgkmcnt(7)
	v_mfma_f32_16x16x32_bf16 v[148:151], v[212:215], v[64:67], v[236:239]
	v_mfma_f32_16x16x32_bf16 v[152:155], v[212:215], v[88:91], v[240:243]
	ds_read_b128 v[212:215], v193 offset:13440
	s_waitcnt lgkmcnt(7)
	v_mfma_f32_16x16x32_bf16 v[156:159], v[216:219], v[64:67], v[236:239]
	v_mfma_f32_16x16x32_bf16 v[160:163], v[216:219], v[88:91], v[240:243]
	ds_read_b128 v[216:219], v193 offset:20096
	s_waitcnt lgkmcnt(7)
	v_mfma_f32_16x16x32_bf16 v[132:135], v[220:223], v[68:71], v[132:135]
	v_mfma_f32_16x16x32_bf16 v[136:139], v[220:223], v[92:95], v[136:139]
	ds_read_b128 v[220:223], v193 offset:192
	s_waitcnt lgkmcnt(7)
	v_mfma_f32_16x16x32_bf16 v[140:143], v[224:227], v[68:71], v[140:143]
	v_mfma_f32_16x16x32_bf16 v[144:147], v[224:227], v[92:95], v[144:147]
	ds_read_b128 v[224:227], v193 offset:6848
	s_waitcnt lgkmcnt(7)
	v_mfma_f32_16x16x32_bf16 v[148:151], v[228:231], v[68:71], v[148:151]
	v_mfma_f32_16x16x32_bf16 v[152:155], v[228:231], v[92:95], v[152:155]
	ds_read_b128 v[228:231], v193 offset:13504
	s_waitcnt lgkmcnt(7)
	v_mfma_f32_16x16x32_bf16 v[156:159], v[232:235], v[68:71], v[156:159]
	v_mfma_f32_16x16x32_bf16 v[160:163], v[232:235], v[92:95], v[160:163]
	ds_read_b128 v[232:235], v193 offset:20160
	s_waitcnt lgkmcnt(7)
	v_mfma_f32_16x16x32_bf16 v[132:135], v[204:207], v[72:75], v[132:135]
	v_mfma_f32_16x16x32_bf16 v[136:139], v[204:207], v[96:99], v[136:139]
	ds_read_b128 v[204:207], v193 offset:256
	s_waitcnt lgkmcnt(7)
	v_mfma_f32_16x16x32_bf16 v[140:143], v[208:211], v[72:75], v[140:143]
	v_mfma_f32_16x16x32_bf16 v[144:147], v[208:211], v[96:99], v[144:147]
	ds_read_b128 v[208:211], v193 offset:6912
	s_waitcnt lgkmcnt(7)
	v_mfma_f32_16x16x32_bf16 v[148:151], v[212:215], v[72:75], v[148:151]
	v_mfma_f32_16x16x32_bf16 v[152:155], v[212:215], v[96:99], v[152:155]
	ds_read_b128 v[212:215], v193 offset:13568
	s_waitcnt lgkmcnt(7)
	v_mfma_f32_16x16x32_bf16 v[156:159], v[216:219], v[72:75], v[156:159]
	v_mfma_f32_16x16x32_bf16 v[160:163], v[216:219], v[96:99], v[160:163]
	ds_read_b128 v[216:219], v193 offset:20224
	s_waitcnt lgkmcnt(7)
	v_mfma_f32_16x16x32_bf16 v[132:135], v[220:223], v[76:79], v[132:135]
	v_mfma_f32_16x16x32_bf16 v[136:139], v[220:223], v[100:103], v[136:139]
	ds_read_b128 v[220:223], v193 offset:320
	s_waitcnt lgkmcnt(7)
	v_mfma_f32_16x16x32_bf16 v[140:143], v[224:227], v[76:79], v[140:143]
	v_mfma_f32_16x16x32_bf16 v[144:147], v[224:227], v[100:103], v[144:147]
	ds_read_b128 v[224:227], v193 offset:6976
	s_waitcnt lgkmcnt(7)
	v_mfma_f32_16x16x32_bf16 v[148:151], v[228:231], v[76:79], v[148:151]
	v_mfma_f32_16x16x32_bf16 v[152:155], v[228:231], v[100:103], v[152:155]
	ds_read_b128 v[228:231], v193 offset:13632
	s_waitcnt lgkmcnt(7)
	v_mfma_f32_16x16x32_bf16 v[156:159], v[232:235], v[76:79], v[156:159]
	v_mfma_f32_16x16x32_bf16 v[160:163], v[232:235], v[100:103], v[160:163]
	ds_read_b128 v[232:235], v193 offset:20288
	s_waitcnt lgkmcnt(7)
	v_mfma_f32_16x16x32_bf16 v[132:135], v[204:207], v[80:83], v[132:135]
	v_mfma_f32_16x16x32_bf16 v[136:139], v[204:207], v[104:107], v[136:139]
	ds_read_b128 v[204:207], v252
	s_waitcnt lgkmcnt(7)
	v_mfma_f32_16x16x32_bf16 v[140:143], v[208:211], v[80:83], v[140:143]
	v_mfma_f32_16x16x32_bf16 v[144:147], v[208:211], v[104:107], v[144:147]
	ds_read_b128 v[208:211], v252 offset:64
	s_waitcnt lgkmcnt(7)
	v_mfma_f32_16x16x32_bf16 v[148:151], v[212:215], v[80:83], v[148:151]
	v_mfma_f32_16x16x32_bf16 v[152:155], v[212:215], v[104:107], v[152:155]
	ds_read_b128 v[212:215], v252 offset:2560
	s_waitcnt lgkmcnt(7)
	v_mfma_f32_16x16x32_bf16 v[156:159], v[216:219], v[80:83], v[156:159]
	v_mfma_f32_16x16x32_bf16 v[160:163], v[216:219], v[104:107], v[160:163]
	ds_read_b128 v[216:219], v252 offset:2624
	s_waitcnt lgkmcnt(7)
	v_mfma_f32_16x16x32_bf16 v[132:135], v[220:223], v[84:87], v[132:135]
	v_mfma_f32_16x16x32_bf16 v[136:139], v[220:223], v[108:111], v[136:139]
	ds_read_b128 v[220:223], v252 offset:5120
	s_waitcnt lgkmcnt(7)
	v_mfma_f32_16x16x32_bf16 v[140:143], v[224:227], v[84:87], v[140:143]
	v_mfma_f32_16x16x32_bf16 v[144:147], v[224:227], v[108:111], v[144:147]
	ds_read_b128 v[224:227], v252 offset:5184
	s_waitcnt lgkmcnt(7)
	v_mfma_f32_16x16x32_bf16 v[148:151], v[228:231], v[84:87], v[148:151]
	v_mfma_f32_16x16x32_bf16 v[152:155], v[228:231], v[108:111], v[152:155]
	ds_read_b128 v[228:231], v252 offset:7680
	s_waitcnt lgkmcnt(7)
	v_mfma_f32_16x16x32_bf16 v[156:159], v[232:235], v[84:87], v[156:159]
	v_mfma_f32_16x16x32_bf16 v[160:163], v[232:235], v[108:111], v[160:163]
	ds_read_b128 v[232:235], v252 offset:7744
	s_setprio 1
	s_nop 6
	v_max3_f32 v199, v132, v133, v134
	v_max3_f32 v200, v136, v137, v138
	v_max3_f32 v199, v199, v135, v140
	v_max3_f32 v200, v200, v139, v144
	v_max3_f32 v199, v199, v141, v142
	v_max3_f32 v200, v200, v145, v146
	v_max3_f32 v199, v199, v143, v148
	v_max3_f32 v200, v200, v147, v152
	v_max3_f32 v199, v199, v149, v150
	v_max3_f32 v200, v200, v153, v154
	v_max3_f32 v199, v199, v151, v156
	v_max3_f32 v200, v200, v155, v160
	v_max3_f32 v199, v199, v157, v158
	v_max3_f32 v200, v200, v161, v162
	v_max_f32_e32 v199, v199, v159
	v_max_f32_e32 v200, v200, v163
	v_mov_b32_e32 v253, v199
	v_mov_b32_e32 v201, v200
	s_nop 1
	v_permlane16_swap_b32_e32 v199, v253
	v_permlane16_swap_b32_e32 v200, v201
	s_nop 0
	v_max_f32_e32 v199, v199, v253
	v_max_f32_e32 v200, v200, v201
	v_mov_b32_e32 v253, v199
	v_mov_b32_e32 v201, v200
	s_nop 1
	v_permlane32_swap_b32_e32 v199, v253
	v_permlane32_swap_b32_e32 v200, v201
	s_nop 0
	v_max_f32_e32 v199, v199, v253
	v_max_f32_e32 v200, v200, v201
	v_max_f32_e32 v253, v199, v200
	v_cmp_lt_f32_e32 vcc, v244, v253
	s_cbranch_vccz .Lat_fast_B0
	v_cmp_lt_f32_e32 vcc, v244, v199
	s_nop 1
	v_cndmask_b32_e32 v199, 0, v199, vcc
	v_max_f32_e32 v182, 0, v199
	v_exp_f32_e64 v182, -v182
	v_sub_f32_e32 v132, v132, v199
	v_sub_f32_e32 v133, v133, v199
	v_sub_f32_e32 v134, v134, v199
	v_sub_f32_e32 v135, v135, v199
	v_sub_f32_e32 v140, v140, v199
	v_sub_f32_e32 v141, v141, v199
	v_sub_f32_e32 v142, v142, v199
	v_sub_f32_e32 v143, v143, v199
	v_sub_f32_e32 v148, v148, v199
	v_sub_f32_e32 v149, v149, v199
	v_sub_f32_e32 v150, v150, v199
	v_sub_f32_e32 v151, v151, v199
	v_sub_f32_e32 v156, v156, v199
	v_sub_f32_e32 v157, v157, v199
	v_sub_f32_e32 v158, v158, v199
	v_sub_f32_e32 v159, v159, v199
	v_sub_f32_e32 v236, v236, v199
	v_sub_f32_e32 v237, v237, v199
	v_sub_f32_e32 v238, v238, v199
	v_sub_f32_e32 v239, v239, v199
	v_pk_mul_f32 v[0:1], v[0:1], v[182:183] op_sel_hi:[1,0]
	v_pk_mul_f32 v[2:3], v[2:3], v[182:183] op_sel_hi:[1,0]
	v_pk_mul_f32 v[8:9], v[8:9], v[182:183] op_sel_hi:[1,0]
	v_pk_mul_f32 v[10:11], v[10:11], v[182:183] op_sel_hi:[1,0]
	v_pk_mul_f32 v[16:17], v[16:17], v[182:183] op_sel_hi:[1,0]
	v_pk_mul_f32 v[18:19], v[18:19], v[182:183] op_sel_hi:[1,0]
	v_pk_mul_f32 v[24:25], v[24:25], v[182:183] op_sel_hi:[1,0]
	v_pk_mul_f32 v[26:27], v[26:27], v[182:183] op_sel_hi:[1,0]
	v_pk_mul_f32 v[32:33], v[32:33], v[182:183] op_sel_hi:[1,0]
	v_pk_mul_f32 v[34:35], v[34:35], v[182:183] op_sel_hi:[1,0]
	v_pk_mul_f32 v[40:41], v[40:41], v[182:183] op_sel_hi:[1,0]
	v_pk_mul_f32 v[42:43], v[42:43], v[182:183] op_sel_hi:[1,0]
	v_pk_mul_f32 v[48:49], v[48:49], v[182:183] op_sel_hi:[1,0]
	v_pk_mul_f32 v[50:51], v[50:51], v[182:183] op_sel_hi:[1,0]
	v_pk_mul_f32 v[56:57], v[56:57], v[182:183] op_sel_hi:[1,0]
	v_pk_mul_f32 v[58:59], v[58:59], v[182:183] op_sel_hi:[1,0]
	v_mul_f32_e32 v179, v179, v182
	v_cmp_lt_f32_e32 vcc, v244, v200
	s_nop 1
	v_cndmask_b32_e32 v200, 0, v200, vcc
	v_max_f32_e32 v202, 0, v200
	v_exp_f32_e64 v202, -v202
	v_sub_f32_e32 v136, v136, v200
	v_sub_f32_e32 v137, v137, v200
	v_sub_f32_e32 v138, v138, v200
	v_sub_f32_e32 v139, v139, v200
	v_sub_f32_e32 v144, v144, v200
	v_sub_f32_e32 v145, v145, v200
	v_sub_f32_e32 v146, v146, v200
	v_sub_f32_e32 v147, v147, v200
	v_sub_f32_e32 v152, v152, v200
	v_sub_f32_e32 v153, v153, v200
	v_sub_f32_e32 v154, v154, v200
	v_sub_f32_e32 v155, v155, v200
	v_sub_f32_e32 v160, v160, v200
	v_sub_f32_e32 v161, v161, v200
	v_sub_f32_e32 v162, v162, v200
	v_sub_f32_e32 v163, v163, v200
	v_sub_f32_e32 v240, v240, v200
	v_sub_f32_e32 v241, v241, v200
	v_sub_f32_e32 v242, v242, v200
	v_sub_f32_e32 v243, v243, v200
	v_pk_mul_f32 v[4:5], v[4:5], v[202:203] op_sel_hi:[1,0]
	v_pk_mul_f32 v[6:7], v[6:7], v[202:203] op_sel_hi:[1,0]
	v_pk_mul_f32 v[12:13], v[12:13], v[202:203] op_sel_hi:[1,0]
	v_pk_mul_f32 v[14:15], v[14:15], v[202:203] op_sel_hi:[1,0]
	v_pk_mul_f32 v[20:21], v[20:21], v[202:203] op_sel_hi:[1,0]
	v_pk_mul_f32 v[22:23], v[22:23], v[202:203] op_sel_hi:[1,0]
	v_pk_mul_f32 v[28:29], v[28:29], v[202:203] op_sel_hi:[1,0]
	v_pk_mul_f32 v[30:31], v[30:31], v[202:203] op_sel_hi:[1,0]
	v_pk_mul_f32 v[36:37], v[36:37], v[202:203] op_sel_hi:[1,0]
	v_pk_mul_f32 v[38:39], v[38:39], v[202:203] op_sel_hi:[1,0]
	v_pk_mul_f32 v[44:45], v[44:45], v[202:203] op_sel_hi:[1,0]
	v_pk_mul_f32 v[46:47], v[46:47], v[202:203] op_sel_hi:[1,0]
	v_pk_mul_f32 v[52:53], v[52:53], v[202:203] op_sel_hi:[1,0]
	v_pk_mul_f32 v[54:55], v[54:55], v[202:203] op_sel_hi:[1,0]
	v_pk_mul_f32 v[60:61], v[60:61], v[202:203] op_sel_hi:[1,0]
	v_pk_mul_f32 v[62:63], v[62:63], v[202:203] op_sel_hi:[1,0]
	v_mul_f32_e32 v180, v180, v202
	v_mov_b32_e32 v244, 0x41000000
.Lat_fast_B0:
	v_exp_f32_e32 v132, v132
	v_exp_f32_e32 v136, v136
	v_exp_f32_e32 v133, v133
	v_exp_f32_e32 v137, v137
	v_exp_f32_e32 v134, v134
	v_exp_f32_e32 v138, v138
	v_exp_f32_e32 v135, v135
	v_exp_f32_e32 v139, v139
	v_exp_f32_e32 v140, v140
	v_exp_f32_e32 v144, v144
	v_exp_f32_e32 v141, v141
	v_exp_f32_e32 v145, v145
	v_exp_f32_e32 v142, v142
	v_exp_f32_e32 v146, v146
	v_exp_f32_e32 v143, v143
	v_exp_f32_e32 v147, v147
	v_exp_f32_e32 v148, v148
	v_exp_f32_e32 v152, v152
	v_exp_f32_e32 v149, v149
	v_exp_f32_e32 v153, v153
	v_exp_f32_e32 v150, v150
	v_exp_f32_e32 v154, v154
	v_exp_f32_e32 v151, v151
	v_exp_f32_e32 v155, v155
	v_exp_f32_e32 v156, v156
	v_exp_f32_e32 v160, v160
	v_exp_f32_e32 v157, v157
	v_exp_f32_e32 v161, v161
	v_exp_f32_e32 v158, v158
	v_exp_f32_e32 v162, v162
	v_exp_f32_e32 v159, v159
	v_exp_f32_e32 v163, v163
	v_add_f32_e32 v183, v132, v133
	v_add_f32_e32 v203, v136, v137
	v_add_f32_e32 v183, v183, v134
	v_add_f32_e32 v203, v203, v138
	v_add_f32_e32 v183, v183, v135
	v_add_f32_e32 v203, v203, v139
	v_add_f32_e32 v183, v183, v140
	v_add_f32_e32 v203, v203, v144
	v_add_f32_e32 v183, v183, v141
	v_add_f32_e32 v203, v203, v145
	v_add_f32_e32 v183, v183, v142
	v_add_f32_e32 v203, v203, v146
	v_add_f32_e32 v183, v183, v143
	v_add_f32_e32 v203, v203, v147
	v_add_f32_e32 v183, v183, v148
	v_add_f32_e32 v203, v203, v152
	v_add_f32_e32 v183, v183, v149
	v_add_f32_e32 v203, v203, v153
	v_add_f32_e32 v183, v183, v150
	v_add_f32_e32 v203, v203, v154
	v_add_f32_e32 v183, v183, v151
	v_add_f32_e32 v203, v203, v155
	v_add_f32_e32 v183, v183, v156
	v_add_f32_e32 v203, v203, v160
	v_add_f32_e32 v183, v183, v157
	v_add_f32_e32 v203, v203, v161
	v_add_f32_e32 v183, v183, v158
	v_add_f32_e32 v203, v203, v162
	v_add_f32_e32 v183, v183, v159
	v_add_f32_e32 v203, v203, v163
	v_add_f32_e32 v179, v179, v183
	v_add_f32_e32 v180, v180, v203
	v_cvt_pk_bf16_f32 v132, v132, v133
	v_cvt_pk_bf16_f32 v133, v134, v135
	v_cvt_pk_bf16_f32 v134, v140, v141
	v_cvt_pk_bf16_f32 v135, v142, v143
	v_cvt_pk_bf16_f32 v136, v136, v137
	v_cvt_pk_bf16_f32 v137, v138, v139
	v_cvt_pk_bf16_f32 v138, v144, v145
	v_cvt_pk_bf16_f32 v139, v146, v147
	v_cvt_pk_bf16_f32 v148, v148, v149
	v_cvt_pk_bf16_f32 v149, v150, v151
	v_cvt_pk_bf16_f32 v150, v156, v157
	v_cvt_pk_bf16_f32 v151, v158, v159
	v_cvt_pk_bf16_f32 v152, v152, v153
	v_cvt_pk_bf16_f32 v153, v154, v155
	v_cvt_pk_bf16_f32 v154, v160, v161
	v_cvt_pk_bf16_f32 v155, v162, v163
	s_cmpk_lt_u32 s35, 67
	s_cbranch_scc0 .Lat_nostage_B0
	s_xor_b32 s12, s44, 26624
	v_add_u32_e32 v195, s12, v169
	v_add_u32_e32 v196, s12, v170
	v_add_u32_e32 v197, s13, v171
	v_add_u32_e32 v198, 10240, v197
	s_waitcnt vmcnt(0)
	ds_write_b128 v195, v[112:115]
	ds_write_b128 v195, v[116:119] offset:13312
	ds_write_b128 v196, v[120:123]
	ds_write2_b64 v197, v[124:125], v[126:127] offset1:2
	ds_write2_b64 v198, v[128:129], v[130:131] offset1:2

.Lat_noload_B:
	v_add_u32_e32 v193, s44, v164
	v_add_u32_e32 v194, s0, v168
	v_add_u32_e32 v252, s1, v168
	s_setprio 0
	s_nop 0
	v_mfma_f32_16x16x32_bf16 v[0:3], v[204:207], v[132:135], v[0:3]
	v_mfma_f32_16x16x32_bf16 v[4:7], v[204:207], v[136:139], v[4:7]
	ds_read_b128 v[204:207], v194 offset:10240
	v_mfma_f32_16x16x32_bf16 v[0:3], v[208:211], v[148:151], v[0:3]
	v_mfma_f32_16x16x32_bf16 v[4:7], v[208:211], v[152:155], v[4:7]
	ds_read_b128 v[208:211], v194 offset:10304
	v_mfma_f32_16x16x32_bf16 v[8:11], v[212:215], v[132:135], v[8:11]
	v_mfma_f32_16x16x32_bf16 v[12:15], v[212:215], v[136:139], v[12:15]
	ds_read_b128 v[212:215], v194 offset:12800
	v_mfma_f32_16x16x32_bf16 v[8:11], v[216:219], v[148:151], v[8:11]
	v_mfma_f32_16x16x32_bf16 v[12:15], v[216:219], v[152:155], v[12:15]
	ds_read_b128 v[216:219], v194 offset:12864
	v_mfma_f32_16x16x32_bf16 v[16:19], v[220:223], v[132:135], v[16:19]
	v_mfma_f32_16x16x32_bf16 v[20:23], v[220:223], v[136:139], v[20:23]
	ds_read_b128 v[220:223], v194 offset:15360
	v_mfma_f32_16x16x32_bf16 v[16:19], v[224:227], v[148:151], v[16:19]
	v_mfma_f32_16x16x32_bf16 v[20:23], v[224:227], v[152:155], v[20:23]
	ds_read_b128 v[224:227], v194 offset:15424
	v_mfma_f32_16x16x32_bf16 v[24:27], v[228:231], v[132:135], v[24:27]
	v_mfma_f32_16x16x32_bf16 v[28:31], v[228:231], v[136:139], v[28:31]
	ds_read_b128 v[228:231], v194 offset:17920
	v_mfma_f32_16x16x32_bf16 v[24:27], v[232:235], v[148:151], v[24:27]
	v_mfma_f32_16x16x32_bf16 v[28:31], v[232:235], v[152:155], v[28:31]
	ds_read_b128 v[232:235], v194 offset:17984
	s_waitcnt lgkmcnt(7)
	v_mfma_f32_16x16x32_bf16 v[32:35], v[204:207], v[132:135], v[32:35]
	v_mfma_f32_16x16x32_bf16 v[36:39], v[204:207], v[136:139], v[36:39]
	ds_read_b128 v[204:207], v193
	s_waitcnt lgkmcnt(7)
	v_mfma_f32_16x16x32_bf16 v[32:35], v[208:211], v[148:151], v[32:35]
	v_mfma_f32_16x16x32_bf16 v[36:39], v[208:211], v[152:155], v[36:39]
	ds_read_b128 v[208:211], v193 offset:6656
	s_waitcnt lgkmcnt(7)
	v_mfma_f32_16x16x32_bf16 v[40:43], v[212:215], v[132:135], v[40:43]
	v_mfma_f32_16x16x32_bf16 v[44:47], v[212:215], v[136:139], v[44:47]
	ds_read_b128 v[212:215], v193 offset:13312
	s_waitcnt lgkmcnt(7)
	v_mfma_f32_16x16x32_bf16 v[40:43], v[216:219], v[148:151], v[40:43]
	v_mfma_f32_16x16x32_bf16 v[44:47], v[216:219], v[152:155], v[44:47]
	ds_read_b128 v[216:219], v193 offset:19968
	s_waitcnt lgkmcnt(7)
	v_mfma_f32_16x16x32_bf16 v[48:51], v[220:223], v[132:135], v[48:51]
	v_mfma_f32_16x16x32_bf16 v[52:55], v[220:223], v[136:139], v[52:55]
	ds_read_b128 v[220:223], v193 offset:64
	s_waitcnt lgkmcnt(7)
	v_mfma_f32_16x16x32_bf16 v[48:51], v[224:227], v[148:151], v[48:51]
	v_mfma_f32_16x16x32_bf16 v[52:55], v[224:227], v[152:155], v[52:55]
	ds_read_b128 v[224:227], v193 offset:6720
	s_waitcnt lgkmcnt(7)
	v_mfma_f32_16x16x32_bf16 v[56:59], v[228:231], v[132:135], v[56:59]
	v_mfma_f32_16x16x32_bf16 v[60:63], v[228:231], v[136:139], v[60:63]
	ds_read_b128 v[228:231], v193 offset:13376
	s_waitcnt lgkmcnt(7)
	v_mfma_f32_16x16x32_bf16 v[56:59], v[232:235], v[148:151], v[56:59]
	v_mfma_f32_16x16x32_bf16 v[60:63], v[232:235], v[152:155], v[60:63]
	ds_read_b128 v[232:235], v193 offset:20032
	s_setprio 1
	s_setprio 0
	s_waitcnt lgkmcnt(7)
	v_mfma_f32_16x16x32_bf16 v[132:135], v[204:207], v[64:67], v[236:239]
	v_mfma_f32_16x16x32_bf16 v[136:139], v[204:207], v[88:91], v[240:243]
	ds_read_b128 v[204:207], v193 offset:128
	s_waitcnt lgkmcnt(7)
	v_mfma_f32_16x16x32_bf16 v[140:143], v[208:211], v[64:67], v[236:239]
	v_mfma_f32_16x16x32_bf16 v[144:147], v[208:211], v[88:91], v[240:243]
	ds_read_b128 v[208:211], v193 offset:6784
	s_waitcnt lgkmcnt(7)
	v_mfma_f32_16x16x32_bf16 v[148:151], v[212:215], v[64:67], v[236:239]
	v_mfma_f32_16x16x32_bf16 v[152:155], v[212:215], v[88:91], v[240:243]
	ds_read_b128 v[212:215], v193 offset:13440
	s_waitcnt lgkmcnt(7)
	v_mfma_f32_16x16x32_bf16 v[156:159], v[216:219], v[64:67], v[236:239]
	v_mfma_f32_16x16x32_bf16 v[160:163], v[216:219], v[88:91], v[240:243]
	ds_read_b128 v[216:219], v193 offset:20096
	s_waitcnt lgkmcnt(7)
	v_mfma_f32_16x16x32_bf16 v[132:135], v[220:223], v[68:71], v[132:135]
	v_mfma_f32_16x16x32_bf16 v[136:139], v[220:223], v[92:95], v[136:139]
	ds_read_b128 v[220:223], v193 offset:192
	s_waitcnt lgkmcnt(7)
	v_mfma_f32_16x16x32_bf16 v[140:143], v[224:227], v[68:71], v[140:143]
	v_mfma_f32_16x16x32_bf16 v[144:147], v[224:227], v[92:95], v[144:147]
	ds_read_b128 v[224:227], v193 offset:6848
	s_waitcnt lgkmcnt(7)
	v_mfma_f32_16x16x32_bf16 v[148:151], v[228:231], v[68:71], v[148:151]
	v_mfma_f32_16x16x32_bf16 v[152:155], v[228:231], v[92:95], v[152:155]
	ds_read_b128 v[228:231], v193 offset:13504
	s_waitcnt lgkmcnt(7)
	v_mfma_f32_16x16x32_bf16 v[156:159], v[232:235], v[68:71], v[156:159]
	v_mfma_f32_16x16x32_bf16 v[160:163], v[232:235], v[92:95], v[160:163]
	ds_read_b128 v[232:235], v193 offset:20160
	s_waitcnt lgkmcnt(7)
	v_mfma_f32_16x16x32_bf16 v[132:135], v[204:207], v[72:75], v[132:135]
	v_mfma_f32_16x16x32_bf16 v[136:139], v[204:207], v[96:99], v[136:139]
	ds_read_b128 v[204:207], v193 offset:256
	s_waitcnt lgkmcnt(7)
	v_mfma_f32_16x16x32_bf16 v[140:143], v[208:211], v[72:75], v[140:143]
	v_mfma_f32_16x16x32_bf16 v[144:147], v[208:211], v[96:99], v[144:147]
	ds_read_b128 v[208:211], v193 offset:6912
	s_waitcnt lgkmcnt(7)
	v_mfma_f32_16x16x32_bf16 v[148:151], v[212:215], v[72:75], v[148:151]
	v_mfma_f32_16x16x32_bf16 v[152:155], v[212:215], v[96:99], v[152:155]
	ds_read_b128 v[212:215], v193 offset:13568
	s_waitcnt lgkmcnt(7)
	v_mfma_f32_16x16x32_bf16 v[156:159], v[216:219], v[72:75], v[156:159]
	v_mfma_f32_16x16x32_bf16 v[160:163], v[216:219], v[96:99], v[160:163]
	ds_read_b128 v[216:219], v193 offset:20224
	s_waitcnt lgkmcnt(7)
	v_mfma_f32_16x16x32_bf16 v[132:135], v[220:223], v[76:79], v[132:135]
	v_mfma_f32_16x16x32_bf16 v[136:139], v[220:223], v[100:103], v[136:139]
	ds_read_b128 v[220:223], v193 offset:320
	s_waitcnt lgkmcnt(7)
	v_mfma_f32_16x16x32_bf16 v[140:143], v[224:227], v[76:79], v[140:143]
	v_mfma_f32_16x16x32_bf16 v[144:147], v[224:227], v[100:103], v[144:147]
	ds_read_b128 v[224:227], v193 offset:6976
	s_waitcnt lgkmcnt(7)
	v_mfma_f32_16x16x32_bf16 v[148:151], v[228:231], v[76:79], v[148:151]
	v_mfma_f32_16x16x32_bf16 v[152:155], v[228:231], v[100:103], v[152:155]
	ds_read_b128 v[228:231], v193 offset:13632
	s_waitcnt lgkmcnt(7)
	v_mfma_f32_16x16x32_bf16 v[156:159], v[232:235], v[76:79], v[156:159]
	v_mfma_f32_16x16x32_bf16 v[160:163], v[232:235], v[100:103], v[160:163]
	ds_read_b128 v[232:235], v193 offset:20288
	s_waitcnt lgkmcnt(7)
	v_mfma_f32_16x16x32_bf16 v[132:135], v[204:207], v[80:83], v[132:135]
	v_mfma_f32_16x16x32_bf16 v[136:139], v[204:207], v[104:107], v[136:139]
	ds_read_b128 v[204:207], v252
	s_waitcnt lgkmcnt(7)
	v_mfma_f32_16x16x32_bf16 v[140:143], v[208:211], v[80:83], v[140:143]
	v_mfma_f32_16x16x32_bf16 v[144:147], v[208:211], v[104:107], v[144:147]
	ds_read_b128 v[208:211], v252 offset:64
	s_waitcnt lgkmcnt(7)
	v_mfma_f32_16x16x32_bf16 v[148:151], v[212:215], v[80:83], v[148:151]
	v_mfma_f32_16x16x32_bf16 v[152:155], v[212:215], v[104:107], v[152:155]
	ds_read_b128 v[212:215], v252 offset:2560
	s_waitcnt lgkmcnt(7)
	v_mfma_f32_16x16x32_bf16 v[156:159], v[216:219], v[80:83], v[156:159]
	v_mfma_f32_16x16x32_bf16 v[160:163], v[216:219], v[104:107], v[160:163]
	ds_read_b128 v[216:219], v252 offset:2624
	s_waitcnt lgkmcnt(7)
	v_mfma_f32_16x16x32_bf16 v[132:135], v[220:223], v[84:87], v[132:135]
	v_mfma_f32_16x16x32_bf16 v[136:139], v[220:223], v[108:111], v[136:139]
	ds_read_b128 v[220:223], v252 offset:5120
	s_waitcnt lgkmcnt(7)
	v_mfma_f32_16x16x32_bf16 v[140:143], v[224:227], v[84:87], v[140:143]
	v_mfma_f32_16x16x32_bf16 v[144:147], v[224:227], v[108:111], v[144:147]
	ds_read_b128 v[224:227], v252 offset:5184
	s_waitcnt lgkmcnt(7)
	v_mfma_f32_16x16x32_bf16 v[148:151], v[228:231], v[84:87], v[148:151]
	v_mfma_f32_16x16x32_bf16 v[152:155], v[228:231], v[108:111], v[152:155]
	ds_read_b128 v[228:231], v252 offset:7680
	s_waitcnt lgkmcnt(7)
	v_mfma_f32_16x16x32_bf16 v[156:159], v[232:235], v[84:87], v[156:159]
	v_mfma_f32_16x16x32_bf16 v[160:163], v[232:235], v[108:111], v[160:163]
	ds_read_b128 v[232:235], v252 offset:7744
	s_setprio 1
	s_nop 6
	v_max3_f32 v199, v132, v133, v134
	v_max3_f32 v200, v136, v137, v138
	v_max3_f32 v199, v199, v135, v140
	v_max3_f32 v200, v200, v139, v144
	v_max3_f32 v199, v199, v141, v142
	v_max3_f32 v200, v200, v145, v146
	v_max3_f32 v199, v199, v143, v148
	v_max3_f32 v200, v200, v147, v152
	v_max3_f32 v199, v199, v149, v150
	v_max3_f32 v200, v200, v153, v154
	v_max3_f32 v199, v199, v151, v156
	v_max3_f32 v200, v200, v155, v160
	v_max3_f32 v199, v199, v157, v158
	v_max3_f32 v200, v200, v161, v162
	v_max_f32_e32 v199, v199, v159
	v_max_f32_e32 v200, v200, v163
	v_mov_b32_e32 v253, v199
	v_mov_b32_e32 v201, v200
	s_nop 1
	v_permlane16_swap_b32_e32 v199, v253
	v_permlane16_swap_b32_e32 v200, v201
	s_nop 0
	v_max_f32_e32 v199, v199, v253
	v_max_f32_e32 v200, v200, v201
	v_mov_b32_e32 v253, v199
	v_mov_b32_e32 v201, v200
	s_nop 1
	v_permlane32_swap_b32_e32 v199, v253
	v_permlane32_swap_b32_e32 v200, v201
	s_nop 0
	v_max_f32_e32 v199, v199, v253
	v_max_f32_e32 v200, v200, v201
	v_max_f32_e32 v253, v199, v200
	v_cmp_lt_f32_e32 vcc, v244, v253
	s_cbranch_vccz .Lat_fast_B
	v_cmp_lt_f32_e32 vcc, v244, v199
	s_nop 1
	v_cndmask_b32_e32 v199, 0, v199, vcc
	v_max_f32_e32 v182, 0, v199
	v_exp_f32_e64 v182, -v182
	v_sub_f32_e32 v132, v132, v199
	v_sub_f32_e32 v133, v133, v199
	v_sub_f32_e32 v134, v134, v199
	v_sub_f32_e32 v135, v135, v199
	v_sub_f32_e32 v140, v140, v199
	v_sub_f32_e32 v141, v141, v199
	v_sub_f32_e32 v142, v142, v199
	v_sub_f32_e32 v143, v143, v199
	v_sub_f32_e32 v148, v148, v199
	v_sub_f32_e32 v149, v149, v199
	v_sub_f32_e32 v150, v150, v199
	v_sub_f32_e32 v151, v151, v199
	v_sub_f32_e32 v156, v156, v199
	v_sub_f32_e32 v157, v157, v199
	v_sub_f32_e32 v158, v158, v199
	v_sub_f32_e32 v159, v159, v199
	v_sub_f32_e32 v236, v236, v199
	v_sub_f32_e32 v237, v237, v199
	v_sub_f32_e32 v238, v238, v199
	v_sub_f32_e32 v239, v239, v199
	v_pk_mul_f32 v[0:1], v[0:1], v[182:183] op_sel_hi:[1,0]
	v_pk_mul_f32 v[2:3], v[2:3], v[182:183] op_sel_hi:[1,0]
	v_pk_mul_f32 v[8:9], v[8:9], v[182:183] op_sel_hi:[1,0]
	v_pk_mul_f32 v[10:11], v[10:11], v[182:183] op_sel_hi:[1,0]
	v_pk_mul_f32 v[16:17], v[16:17], v[182:183] op_sel_hi:[1,0]
	v_pk_mul_f32 v[18:19], v[18:19], v[182:183] op_sel_hi:[1,0]
	v_pk_mul_f32 v[24:25], v[24:25], v[182:183] op_sel_hi:[1,0]
	v_pk_mul_f32 v[26:27], v[26:27], v[182:183] op_sel_hi:[1,0]
	v_pk_mul_f32 v[32:33], v[32:33], v[182:183] op_sel_hi:[1,0]
	v_pk_mul_f32 v[34:35], v[34:35], v[182:183] op_sel_hi:[1,0]
	v_pk_mul_f32 v[40:41], v[40:41], v[182:183] op_sel_hi:[1,0]
	v_pk_mul_f32 v[42:43], v[42:43], v[182:183] op_sel_hi:[1,0]
	v_pk_mul_f32 v[48:49], v[48:49], v[182:183] op_sel_hi:[1,0]
	v_pk_mul_f32 v[50:51], v[50:51], v[182:183] op_sel_hi:[1,0]
	v_pk_mul_f32 v[56:57], v[56:57], v[182:183] op_sel_hi:[1,0]
	v_pk_mul_f32 v[58:59], v[58:59], v[182:183] op_sel_hi:[1,0]
	v_mul_f32_e32 v179, v179, v182
	v_cmp_lt_f32_e32 vcc, v244, v200
	s_nop 1
	v_cndmask_b32_e32 v200, 0, v200, vcc
	v_max_f32_e32 v202, 0, v200
	v_exp_f32_e64 v202, -v202
	v_sub_f32_e32 v136, v136, v200
	v_sub_f32_e32 v137, v137, v200
	v_sub_f32_e32 v138, v138, v200
	v_sub_f32_e32 v139, v139, v200
	v_sub_f32_e32 v144, v144, v200
	v_sub_f32_e32 v145, v145, v200
	v_sub_f32_e32 v146, v146, v200
	v_sub_f32_e32 v147, v147, v200
	v_sub_f32_e32 v152, v152, v200
	v_sub_f32_e32 v153, v153, v200
	v_sub_f32_e32 v154, v154, v200
	v_sub_f32_e32 v155, v155, v200
	v_sub_f32_e32 v160, v160, v200
	v_sub_f32_e32 v161, v161, v200
	v_sub_f32_e32 v162, v162, v200
	v_sub_f32_e32 v163, v163, v200
	v_sub_f32_e32 v240, v240, v200
	v_sub_f32_e32 v241, v241, v200
	v_sub_f32_e32 v242, v242, v200
	v_sub_f32_e32 v243, v243, v200
	v_pk_mul_f32 v[4:5], v[4:5], v[202:203] op_sel_hi:[1,0]
	v_pk_mul_f32 v[6:7], v[6:7], v[202:203] op_sel_hi:[1,0]
	v_pk_mul_f32 v[12:13], v[12:13], v[202:203] op_sel_hi:[1,0]
	v_pk_mul_f32 v[14:15], v[14:15], v[202:203] op_sel_hi:[1,0]
	v_pk_mul_f32 v[20:21], v[20:21], v[202:203] op_sel_hi:[1,0]
	v_pk_mul_f32 v[22:23], v[22:23], v[202:203] op_sel_hi:[1,0]
	v_pk_mul_f32 v[28:29], v[28:29], v[202:203] op_sel_hi:[1,0]
	v_pk_mul_f32 v[30:31], v[30:31], v[202:203] op_sel_hi:[1,0]
	v_pk_mul_f32 v[36:37], v[36:37], v[202:203] op_sel_hi:[1,0]
	v_pk_mul_f32 v[38:39], v[38:39], v[202:203] op_sel_hi:[1,0]
	v_pk_mul_f32 v[44:45], v[44:45], v[202:203] op_sel_hi:[1,0]
	v_pk_mul_f32 v[46:47], v[46:47], v[202:203] op_sel_hi:[1,0]
	v_pk_mul_f32 v[52:53], v[52:53], v[202:203] op_sel_hi:[1,0]
	v_pk_mul_f32 v[54:55], v[54:55], v[202:203] op_sel_hi:[1,0]
	v_pk_mul_f32 v[60:61], v[60:61], v[202:203] op_sel_hi:[1,0]
	v_pk_mul_f32 v[62:63], v[62:63], v[202:203] op_sel_hi:[1,0]
	v_mul_f32_e32 v180, v180, v202
	v_mov_b32_e32 v244, 0x41000000

.Lat_nostage_B:
	s_xor_b32 s44, s44, 26624
	s_mov_b32 s12, s0
	s_mov_b32 s0, s1
	s_mov_b32 s1, s13
	s_mov_b32 s13, s12
	s_add_u32 s35, s35, 1
	s_waitcnt lgkmcnt(0)
	s_barrier
	s_cmpk_lt_u32 s35, 68
	s_cbranch_scc1 .Lat_B_loop
	v_add_u32_e32 v194, s0, v168
	s_setprio 0
	s_nop 0
	v_mfma_f32_16x16x32_bf16 v[0:3], v[204:207], v[132:135], v[0:3]
	v_mfma_f32_16x16x32_bf16 v[4:7], v[204:207], v[136:139], v[4:7]
	ds_read_b128 v[204:207], v194 offset:10240
	v_mfma_f32_16x16x32_bf16 v[0:3], v[208:211], v[148:151], v[0:3]
	v_mfma_f32_16x16x32_bf16 v[4:7], v[208:211], v[152:155], v[4:7]
	ds_read_b128 v[208:211], v194 offset:10304
	v_mfma_f32_16x16x32_bf16 v[8:11], v[212:215], v[132:135], v[8:11]
	v_mfma_f32_16x16x32_bf16 v[12:15], v[212:215], v[136:139], v[12:15]
	ds_read_b128 v[212:215], v194 offset:12800
	v_mfma_f32_16x16x32_bf16 v[8:11], v[216:219], v[148:151], v[8:11]
	v_mfma_f32_16x16x32_bf16 v[12:15], v[216:219], v[152:155], v[12:15]
	ds_read_b128 v[216:219], v194 offset:12864
	v_mfma_f32_16x16x32_bf16 v[16:19], v[220:223], v[132:135], v[16:19]
	v_mfma_f32_16x16x32_bf16 v[20:23], v[220:223], v[136:139], v[20:23]
	ds_read_b128 v[220:223], v194 offset:15360
	v_mfma_f32_16x16x32_bf16 v[16:19], v[224:227], v[148:151], v[16:19]
	v_mfma_f32_16x16x32_bf16 v[20:23], v[224:227], v[152:155], v[20:23]
	ds_read_b128 v[224:227], v194 offset:15424
	v_mfma_f32_16x16x32_bf16 v[24:27], v[228:231], v[132:135], v[24:27]
	v_mfma_f32_16x16x32_bf16 v[28:31], v[228:231], v[136:139], v[28:31]
	ds_read_b128 v[228:231], v194 offset:17920
	v_mfma_f32_16x16x32_bf16 v[24:27], v[232:235], v[148:151], v[24:27]
	v_mfma_f32_16x16x32_bf16 v[28:31], v[232:235], v[152:155], v[28:31]
	ds_read_b128 v[232:235], v194 offset:17984
	s_waitcnt lgkmcnt(7)
	v_mfma_f32_16x16x32_bf16 v[32:35], v[204:207], v[132:135], v[32:35]
	v_mfma_f32_16x16x32_bf16 v[36:39], v[204:207], v[136:139], v[36:39]
	s_waitcnt lgkmcnt(6)
	v_mfma_f32_16x16x32_bf16 v[32:35], v[208:211], v[148:151], v[32:35]
	v_mfma_f32_16x16x32_bf16 v[36:39], v[208:211], v[152:155], v[36:39]
	s_waitcnt lgkmcnt(5)
	v_mfma_f32_16x16x32_bf16 v[40:43], v[212:215], v[132:135], v[40:43]
	v_mfma_f32_16x16x32_bf16 v[44:47], v[212:215], v[136:139], v[44:47]
	s_waitcnt lgkmcnt(4)
	v_mfma_f32_16x16x32_bf16 v[40:43], v[216:219], v[148:151], v[40:43]
	v_mfma_f32_16x16x32_bf16 v[44:47], v[216:219], v[152:155], v[44:47]
	s_waitcnt lgkmcnt(3)
	v_mfma_f32_16x16x32_bf16 v[48:51], v[220:223], v[132:135], v[48:51]
	v_mfma_f32_16x16x32_bf16 v[52:55], v[220:223], v[136:139], v[52:55]
	s_waitcnt lgkmcnt(2)
	v_mfma_f32_16x16x32_bf16 v[48:51], v[224:227], v[148:151], v[48:51]
	v_mfma_f32_16x16x32_bf16 v[52:55], v[224:227], v[152:155], v[52:55]
	s_waitcnt lgkmcnt(1)
	v_mfma_f32_16x16x32_bf16 v[56:59], v[228:231], v[132:135], v[56:59]
	v_mfma_f32_16x16x32_bf16 v[60:63], v[228:231], v[136:139], v[60:63]
	s_waitcnt lgkmcnt(0)
	v_mfma_f32_16x16x32_bf16 v[56:59], v[232:235], v[148:151], v[56:59]
	v_mfma_f32_16x16x32_bf16 v[60:63], v[232:235], v[152:155], v[60:63]
	s_setprio 1
	s_waitcnt lgkmcnt(0)
